# attention key loop shifted by 4 bytes (instruction placement phase test)
# baseline (speedup 1.0000x reference)
; #define LAS __attribute__((address_space(3)))
; __device__ __forceinline__ void attn_unit2(LAS unsigned char* lds, const bf16_t* __restrict__ Q, const bf16_t* __restrict__ KN, const bf16_t* __restrict__ KPE, ...
;     ...
;     f32x16 oa0 = {}, oa1 = {}, ob0 = {}, ob1 = {};
;     float ma = -1.0e30f, mb = -1.0e30f, la = 0.f, lb = 0.f;
;     for (int t = 0; t < ntiles; ++t) {
;         __builtin_amdgcn_sched_barrier(0);
;         f32x16 sa0 = {}, sa1 = {}, sb0 = {}, sb1 = {};
;         const LAS unsigned char* ka = lds + sc + ka_off;
; #pragma unroll
;         for (int ds = 0; ds < 6; ++ds) {
;             const bf16x8 k0 = *(const LAS bf16x8*)(ka + ds * 32);
;             const bf16x8 k1 = *(const LAS bf16x8*)(ka + 32 * KROW + ds * 32);
;             sa0 = __builtin_amdgcn_mfma_f32_32x32x16_bf16(k0, qa[ds], sa0, 0, 0, 0);
;             sa1 = __builtin_amdgcn_mfma_f32_32x32x16_bf16(k1, qa[ds], sa1, 0, 0, 0);
;             sb0 = __builtin_amdgcn_mfma_f32_32x32x16_bf16(k0, qb[ds], sb0, 0, 0, 0);
;             sb1 = __builtin_amdgcn_mfma_f32_32x32x16_bf16(k1, qb[ds], sb1, 0, 0, 0);
;         }
.Lat_noprio:
	v_mov_b32_e32 v96, 0
	v_mov_b32_e32 v97, 0
	v_mov_b32_e32 v98, 0
	v_mov_b32_e32 v99, 0
	v_mov_b32_e32 v100, 0
	v_mov_b32_e32 v101, 0
	v_mov_b32_e32 v102, 0
	v_mov_b32_e32 v103, 0
	v_mov_b32_e32 v112, 0
	v_mov_b32_e32 v113, 0
	v_mov_b32_e32 v114, 0
	v_mov_b32_e32 v115, 0
	v_mov_b32_e32 v116, 0
	v_mov_b32_e32 v117, 0
	v_mov_b32_e32 v118, 0
	v_mov_b32_e32 v119, 0
	v_sub_u32_e32 v228, 1, v192
	v_mul_u32_u24_e32 v228, 0xffff, v228
	v_and_b32_e32 v240, 0x3f80, v228
	v_mov_b32_e32 v241, 0
	v_mov_b32_e32 v242, 0
	v_mov_b32_e32 v243, 0
	v_and_b32_e32 v244, 0x4480, v228
	v_mov_b32_e32 v245, 0
	v_mov_b32_e32 v246, 0
	v_mov_b32_e32 v247, 0
	v_mov_b32_e32 v194, 0xc4800000
	v_and_b32_e32 v248, 0x4480, v228
	v_mov_b32_e32 v249, 0
	v_mov_b32_e32 v250, 0
	v_mov_b32_e32 v251, 0
	v_mov_b32_e32 v195, 0xc4800000
	v_add3_u32 v224, s34, v183, v128
	ds_read_b128 v[212:215], v224 offset:0
	ds_read_b128 v[216:219], v224 offset:32
	ds_read_b128 v[220:223], v224 offset:64
	v_mfma_f32_32x32x16_bf16 v[64:79], v[240:243], v[244:247], 0
	v_mfma_f32_32x32x16_bf16 v[80:95], v[240:243], v[248:251], 0
	s_waitcnt lgkmcnt(2)
	v_mfma_f32_32x32x16_bf16 v[64:79], v[212:215], v[130:133], v[64:79]
	v_mfma_f32_32x32x16_bf16 v[80:95], v[212:215], v[138:141], v[80:95]
	ds_read_b128 v[212:215], v224 offset:96
	s_waitcnt lgkmcnt(2)
	v_mfma_f32_32x32x16_bf16 v[64:79], v[216:219], v[134:137], v[64:79]
	v_mfma_f32_32x32x16_bf16 v[80:95], v[216:219], v[142:145], v[80:95]
	ds_read_b128 v[216:219], v224 offset:128
	s_waitcnt lgkmcnt(2)
	v_mfma_f32_32x32x16_bf16 v[64:79], v[220:223], v[146:149], v[64:79]
	v_mfma_f32_32x32x16_bf16 v[80:95], v[220:223], v[154:157], v[80:95]
	ds_read_b128 v[220:223], v224 offset:160
	s_waitcnt lgkmcnt(2)
	v_mfma_f32_32x32x16_bf16 v[64:79], v[212:215], v[150:153], v[64:79]
	v_mfma_f32_32x32x16_bf16 v[80:95], v[212:215], v[158:161], v[80:95]
	s_waitcnt lgkmcnt(1)
	v_mfma_f32_32x32x16_bf16 v[64:79], v[216:219], v[162:165], v[64:79]
	v_mfma_f32_32x32x16_bf16 v[80:95], v[216:219], v[170:173], v[80:95]
	s_waitcnt lgkmcnt(0)
	v_mfma_f32_32x32x16_bf16 v[64:79], v[220:223], v[166:169], v[64:79]
	v_mfma_f32_32x32x16_bf16 v[80:95], v[220:223], v[174:177], v[80:95]
	v_add3_u32 v225, s34, v187, v128
	ds_read_b128 v[196:199], v225 offset:13376
	ds_read_b128 v[200:203], v225 offset:17984
	ds_read_b128 v[204:207], v225 offset:13408
	ds_read_b128 v[208:211], v225 offset:18016
	s_nop 7
	s_nop 3
	s_nop 0

; __device__ __forceinline__ float xhalf_sum(float m) { auto rr = __builtin_amdgcn_permlane32_swap(__float_as_uint(m), __float_as_uint(m), false, false); return __uint_as_float(rr[0]) + __uint_as_float(rr[1]); }
; __device__ __forceinline__ void attn_unit2(LAS unsigned char* lds, const bf16_t* __restrict__ Q, const bf16_t* __restrict__ KN, const bf16_t* __restrict__ KPE, ...
;     ...
;         { const int tmp = sc; sc = sn; sn = snn; snn = tmp; }
;     }
;     ...
;     const float inva = __builtin_amdgcn_rcpf(xhalf_sum(la)), invb = __builtin_amdgcn_rcpf(xhalf_sum(lb));
.Lat_done:
	s_nop 0
	s_setprio 0
	s_nop 15
